# speedup vs baseline: 1.0005x; 1.0005x over previous
; __device__ __forceinline__ void gemm_tile(const GemmArgs& g, bf16* shm, const int tid, const int wid, char* wsb, const float* gnext) {
;     ...
;   } else {
;     float* C = (float*)g.C; const float* X = (const float*)g.X;
; #pragma unroll
;     for (int ai = 0; ai < 2; ++ai)
; #pragma unroll
;       for (int m = 0; m < 4; ++m) {
;         const int row = ai * HALF + m * 16 + rbase;
;         float* Cr = C + (long)row * g.ldc + cbase; const float* Xr = X + (long)row * g.ldx + cbase;
; #pragma unroll
;         for (int bj = 0; bj < 2; ++bj)
; #pragma unroll
;           for (int n = 0; n < 2; ++n) {
;             f32x4 r = *reinterpret_cast<const f32x4*>(Xr + bj * HALF + n * 16);
;             *reinterpret_cast<f32x4*>(Cr + bj * HALF + n * 16) = r + acc[ai][bj][m][n];
;           }
;       }
;   }
.LBB0_77:
	v_mul_lo_u32 v133, v0, s67
	v_mul_lo_u32 v134, v0, s66
	s_lshl_b32 s0, s67, 6
	s_lshl_b32 s1, s66, 6
	v_add_lshl_u32 v133, v133, v132, 2
	v_add_lshl_u32 v134, v134, v132, 2
	s_mov_b32 s10, s70
	s_mov_b32 s11, s71
	global_load_dwordx4 v[202:205], v133, s[10:11]
	global_load_dwordx4 v[206:209], v133, s[10:11] offset:64
	global_load_dwordx4 v[210:213], v133, s[10:11] offset:512
	global_load_dwordx4 v[214:217], v133, s[10:11] offset:576
	s_mul_i32 s2, s0, 1
	s_add_u32 s10, s70, s2
	s_addc_u32 s11, s71, 0
	global_load_dwordx4 v[218:221], v133, s[10:11]
	global_load_dwordx4 v[222:225], v133, s[10:11] offset:64
	global_load_dwordx4 v[226:229], v133, s[10:11] offset:512
	global_load_dwordx4 v[230:233], v133, s[10:11] offset:576
	s_mul_i32 s2, s0, 2
	s_add_u32 s10, s70, s2
	s_addc_u32 s11, s71, 0
	global_load_dwordx4 v[234:237], v133, s[10:11]
	global_load_dwordx4 v[238:241], v133, s[10:11] offset:64
	global_load_dwordx4 v[242:245], v133, s[10:11] offset:512
	global_load_dwordx4 v[246:249], v133, s[10:11] offset:576
	s_mul_i32 s2, s0, 3
	s_add_u32 s10, s70, s2
	s_addc_u32 s11, s71, 0
	global_load_dwordx4 v[250:253], v133, s[10:11]
	global_load_dwordx4 v[164:167], v133, s[10:11] offset:64
	global_load_dwordx4 v[168:171], v133, s[10:11] offset:512
	global_load_dwordx4 v[172:175], v133, s[10:11] offset:576
	s_waitcnt vmcnt(15)
	v_pk_add_f32 v[204:205], v[126:127], v[204:205]
	v_pk_add_f32 v[202:203], v[124:125], v[202:203]
	s_mov_b32 s16, s68
	s_mov_b32 s17, s69
	global_store_dwordx4 v134, v[202:205], s[16:17]
	s_nop 1
	s_mul_i32 s2, s0, 8
	s_add_u32 s10, s70, s2
	s_addc_u32 s11, s71, 0
	global_load_dwordx4 v[202:205], v133, s[10:11]
	s_waitcnt vmcnt(16)
	v_pk_add_f32 v[208:209], v[118:119], v[208:209]
	v_pk_add_f32 v[206:207], v[116:117], v[206:207]
	global_store_dwordx4 v134, v[206:209], s[16:17] offset:64
	s_nop 1
	global_load_dwordx4 v[206:209], v133, s[10:11] offset:64
	s_waitcnt vmcnt(17)
	v_pk_add_f32 v[212:213], v[130:131], v[212:213]
	v_pk_add_f32 v[210:211], v[128:129], v[210:211]
	global_store_dwordx4 v134, v[210:213], s[16:17] offset:512
	s_nop 1
	global_load_dwordx4 v[210:213], v133, s[10:11] offset:512
	s_waitcnt vmcnt(18)
	v_pk_add_f32 v[216:217], v[122:123], v[216:217]
	v_pk_add_f32 v[214:215], v[120:121], v[214:215]
	global_store_dwordx4 v134, v[214:217], s[16:17] offset:576
	s_nop 1
	global_load_dwordx4 v[214:217], v133, s[10:11] offset:576
	s_waitcnt vmcnt(19)
	v_pk_add_f32 v[220:221], v[110:111], v[220:221]
	v_pk_add_f32 v[218:219], v[108:109], v[218:219]
	s_mul_i32 s2, s1, 1
	s_add_u32 s16, s68, s2
	s_addc_u32 s17, s69, 0
	global_store_dwordx4 v134, v[218:221], s[16:17]
	s_nop 1
	s_mul_i32 s2, s0, 9
	s_add_u32 s10, s70, s2
	s_addc_u32 s11, s71, 0
	global_load_dwordx4 v[218:221], v133, s[10:11]
	s_waitcnt vmcnt(20)
	v_pk_add_f32 v[224:225], v[102:103], v[224:225]
	v_pk_add_f32 v[222:223], v[100:101], v[222:223]
	global_store_dwordx4 v134, v[222:225], s[16:17] offset:64
	s_nop 1
	global_load_dwordx4 v[222:225], v133, s[10:11] offset:64
	s_waitcnt vmcnt(21)
	v_pk_add_f32 v[228:229], v[114:115], v[228:229]
	v_pk_add_f32 v[226:227], v[112:113], v[226:227]
	global_store_dwordx4 v134, v[226:229], s[16:17] offset:512
	s_nop 1
	global_load_dwordx4 v[226:229], v133, s[10:11] offset:512
	s_waitcnt vmcnt(22)
	v_pk_add_f32 v[232:233], v[106:107], v[232:233]
	v_pk_add_f32 v[230:231], v[104:105], v[230:231]
	global_store_dwordx4 v134, v[230:233], s[16:17] offset:576
	s_nop 1
	global_load_dwordx4 v[230:233], v133, s[10:11] offset:576
	s_waitcnt vmcnt(23)
	v_pk_add_f32 v[236:237], v[94:95], v[236:237]
	v_pk_add_f32 v[234:235], v[92:93], v[234:235]
	s_mul_i32 s2, s1, 2
	s_add_u32 s16, s68, s2
	s_addc_u32 s17, s69, 0
	global_store_dwordx4 v134, v[234:237], s[16:17]
	s_nop 1
	s_mul_i32 s2, s0, 10
	s_add_u32 s10, s70, s2
	s_addc_u32 s11, s71, 0
	global_load_dwordx4 v[234:237], v133, s[10:11]
	s_waitcnt vmcnt(24)
	v_pk_add_f32 v[240:241], v[86:87], v[240:241]
	v_pk_add_f32 v[238:239], v[84:85], v[238:239]
	global_store_dwordx4 v134, v[238:241], s[16:17] offset:64
	s_nop 1
	global_load_dwordx4 v[238:241], v133, s[10:11] offset:64
	s_waitcnt vmcnt(25)
	v_pk_add_f32 v[244:245], v[98:99], v[244:245]
	v_pk_add_f32 v[242:243], v[96:97], v[242:243]
	global_store_dwordx4 v134, v[242:245], s[16:17] offset:512
	s_nop 1
	global_load_dwordx4 v[242:245], v133, s[10:11] offset:512
	s_waitcnt vmcnt(26)
; __device__ __forceinline__ void gemm_tile(const GemmArgs& g, bf16* shm, const int tid, const int wid, char* wsb, const float* gnext) {
;     ...
;   } else {
;     float* C = (float*)g.C; const float* X = (const float*)g.X;
; #pragma unroll
;     for (int ai = 0; ai < 2; ++ai)
; #pragma unroll
;       for (int m = 0; m < 4; ++m) {
;         const int row = ai * HALF + m * 16 + rbase;
;         float* Cr = C + (long)row * g.ldc + cbase; const float* Xr = X + (long)row * g.ldx + cbase;
; #pragma unroll
;         for (int bj = 0; bj < 2; ++bj)
; #pragma unroll
;           for (int n = 0; n < 2; ++n) {
;             f32x4 r = *reinterpret_cast<const f32x4*>(Xr + bj * HALF + n * 16);
;             *reinterpret_cast<f32x4*>(Cr + bj * HALF + n * 16) = r + acc[ai][bj][m][n];
;           }
;       }
;   }
	v_pk_add_f32 v[248:249], v[90:91], v[248:249]
	v_pk_add_f32 v[246:247], v[88:89], v[246:247]
	global_store_dwordx4 v134, v[246:249], s[16:17] offset:576
	s_nop 1
	global_load_dwordx4 v[246:249], v133, s[10:11] offset:576
	s_waitcnt vmcnt(27)
	v_pk_add_f32 v[252:253], v[78:79], v[252:253]
	v_pk_add_f32 v[250:251], v[76:77], v[250:251]
	s_mul_i32 s2, s1, 3
	s_add_u32 s16, s68, s2
	s_addc_u32 s17, s69, 0
	global_store_dwordx4 v134, v[250:253], s[16:17]
	s_nop 1
	s_mul_i32 s2, s0, 11
	s_add_u32 s10, s70, s2
	s_addc_u32 s11, s71, 0
	global_load_dwordx4 v[250:253], v133, s[10:11]
	s_waitcnt vmcnt(28)
	v_pk_add_f32 v[166:167], v[70:71], v[166:167]
	v_pk_add_f32 v[164:165], v[68:69], v[164:165]
	global_store_dwordx4 v134, v[164:167], s[16:17] offset:64
	s_nop 1
	global_load_dwordx4 v[164:167], v133, s[10:11] offset:64
	s_waitcnt vmcnt(29)
	v_pk_add_f32 v[170:171], v[82:83], v[170:171]
	v_pk_add_f32 v[168:169], v[80:81], v[168:169]
	global_store_dwordx4 v134, v[168:171], s[16:17] offset:512
	s_nop 1
	global_load_dwordx4 v[168:171], v133, s[10:11] offset:512
	s_waitcnt vmcnt(30)
	v_pk_add_f32 v[174:175], v[74:75], v[174:175]
	v_pk_add_f32 v[172:173], v[72:73], v[172:173]
	global_store_dwordx4 v134, v[172:175], s[16:17] offset:576
	s_nop 1
	global_load_dwordx4 v[172:175], v133, s[10:11] offset:576
	s_waitcnt vmcnt(30)
	v_pk_add_f32 v[204:205], v[66:67], v[204:205]
	v_pk_add_f32 v[202:203], v[64:65], v[202:203]
	s_mul_i32 s2, s1, 8
	s_add_u32 s16, s68, s2
	s_addc_u32 s17, s69, 0
	global_store_dwordx4 v134, v[202:205], s[16:17]
	s_waitcnt vmcnt(29)
	v_pk_add_f32 v[208:209], v[58:59], v[208:209]
	v_pk_add_f32 v[206:207], v[56:57], v[206:207]
	global_store_dwordx4 v134, v[206:209], s[16:17] offset:64
	s_waitcnt vmcnt(28)
	v_pk_add_f32 v[212:213], v[62:63], v[212:213]
	v_pk_add_f32 v[210:211], v[60:61], v[210:211]
	global_store_dwordx4 v134, v[210:213], s[16:17] offset:512
	s_waitcnt vmcnt(27)
	v_pk_add_f32 v[216:217], v[54:55], v[216:217]
	v_pk_add_f32 v[214:215], v[52:53], v[214:215]
	global_store_dwordx4 v134, v[214:217], s[16:17] offset:576
	s_waitcnt vmcnt(26)
	v_pk_add_f32 v[220:221], v[50:51], v[220:221]
	v_pk_add_f32 v[218:219], v[48:49], v[218:219]
	s_mul_i32 s2, s1, 9
	s_add_u32 s16, s68, s2
	s_addc_u32 s17, s69, 0
	global_store_dwordx4 v134, v[218:221], s[16:17]
	s_waitcnt vmcnt(25)
	v_pk_add_f32 v[224:225], v[42:43], v[224:225]
	v_pk_add_f32 v[222:223], v[40:41], v[222:223]
	global_store_dwordx4 v134, v[222:225], s[16:17] offset:64
	s_waitcnt vmcnt(24)
	v_pk_add_f32 v[228:229], v[46:47], v[228:229]
	v_pk_add_f32 v[226:227], v[44:45], v[226:227]
	global_store_dwordx4 v134, v[226:229], s[16:17] offset:512
	s_waitcnt vmcnt(23)
	v_pk_add_f32 v[232:233], v[38:39], v[232:233]
	v_pk_add_f32 v[230:231], v[36:37], v[230:231]
	global_store_dwordx4 v134, v[230:233], s[16:17] offset:576
	s_waitcnt vmcnt(22)
	v_pk_add_f32 v[236:237], v[34:35], v[236:237]
	v_pk_add_f32 v[234:235], v[32:33], v[234:235]
	s_mul_i32 s2, s1, 10
	s_add_u32 s16, s68, s2
	s_addc_u32 s17, s69, 0
	global_store_dwordx4 v134, v[234:237], s[16:17]
	s_waitcnt vmcnt(21)
	v_pk_add_f32 v[240:241], v[26:27], v[240:241]
	v_pk_add_f32 v[238:239], v[24:25], v[238:239]
	global_store_dwordx4 v134, v[238:241], s[16:17] offset:64
	s_waitcnt vmcnt(20)
	v_pk_add_f32 v[244:245], v[30:31], v[244:245]
	v_pk_add_f32 v[242:243], v[28:29], v[242:243]
	global_store_dwordx4 v134, v[242:245], s[16:17] offset:512
	s_waitcnt vmcnt(19)
	v_pk_add_f32 v[248:249], v[22:23], v[248:249]
	v_pk_add_f32 v[246:247], v[20:21], v[246:247]
	global_store_dwordx4 v134, v[246:249], s[16:17] offset:576
	s_waitcnt vmcnt(18)
	v_pk_add_f32 v[252:253], v[18:19], v[252:253]
	v_pk_add_f32 v[250:251], v[16:17], v[250:251]
	s_mul_i32 s2, s1, 11
	s_add_u32 s16, s68, s2
	s_addc_u32 s17, s69, 0
	global_store_dwordx4 v134, v[250:253], s[16:17]
	s_waitcnt vmcnt(17)
	v_pk_add_f32 v[166:167], v[10:11], v[166:167]
	v_pk_add_f32 v[164:165], v[8:9], v[164:165]
	global_store_dwordx4 v134, v[164:167], s[16:17] offset:64
	s_waitcnt vmcnt(16)
	v_pk_add_f32 v[170:171], v[14:15], v[170:171]
	v_pk_add_f32 v[168:169], v[12:13], v[168:169]
	global_store_dwordx4 v134, v[168:171], s[16:17] offset:512
	s_waitcnt vmcnt(15)
	v_pk_add_f32 v[174:175], v[6:7], v[174:175]
	v_pk_add_f32 v[172:173], v[4:5], v[172:173]
	global_store_dwordx4 v134, v[172:175], s[16:17] offset:576
	s_cbranch_execnz .LBB0_34

; __global__ __launch_bounds__(512, 2)
; void hybrid_megakernel(Params p_in) {
;     ...
;           for (int it0 = gw * 4; it0 < (SEQ / 2) * 8; it0 += nw * 4) {
;             f32x4 pv[4], qv[4];
; #pragma unroll
;             for (int u = 0; u < 4; ++u) { const int it = it0 + u, k = it >> 3, n = (it & 7) * 256 + lane * 4;
;               pv[u] = *reinterpret_cast<const f32x4*>(Pp + (long)k * 2048 + n); qv[u] = *reinterpret_cast<const f32x4*>(Qp + (long)k * 2048 + n); }
; #pragma unroll
;             for (int u = 0; u < 4; ++u) { const int it = it0 + u, k = it >> 3, n = (it & 7) * 256 + lane * 4, b = n >> 10, col = n & 1023;
;               const float sg = (k & 1) ? -0.011048543456039806f : 0.011048543456039806f;
;               const f32x4 a4 = {__bfloat162float(ztq[(long)(n + 0) * (2 * SEQ) + SEQ / 2]), __bfloat162float(ztq[(long)(n + 1) * (2 * SEQ) + SEQ / 2]),
;                                 __bfloat162float(ztq[(long)(n + 2) * (2 * SEQ) + SEQ / 2]), __bfloat162float(ztq[(long)(n + 3) * (2 * SEQ) + SEQ / 2])};
;               const f32x4 pc = pv[u] + sg * a4;
;               const f32x4 s1 = pc + qv[u], s2 = pc - qv[u];
;               u32x2 w1 = {cvtpk(s1[0], s1[1]), cvtpk(s1[2], s1[3])};
;               *reinterpret_cast<u32x2*>(fb + ((long)b * SEQ + k) * 1024 + col) = w1;
;               if (k != 0) { u32x2 w2 = {cvtpk(s2[0], s2[1]), cvtpk(s2[2], s2[3])};
;                 *reinterpret_cast<u32x2*>(fb + ((long)b * SEQ + (SEQ - k)) * 1024 + col) = w2; } }
;           }
.LBB0_126:
	s_andn2_b64 vcc, exec, s[0:1]
	s_cbranch_vccnz .LBB0_190
	s_waitcnt lgkmcnt(0)
	s_add_u32 s6, s54, 0x50000000
	s_addc_u32 s7, s55, 0
	s_add_u32 s8, s54, 0x4c000000
	s_addc_u32 s9, s55, 0
	s_cmpk_gt_i32 s60, 0x1fff
	s_movk_i32 s29, 0x2000
	s_cbranch_scc1 .LBB0_138
	s_add_u32 s0, s54, 0x44000000
	s_addc_u32 s1, s55, 0
	s_add_u32 s14, s54, 0x46000000
	s_addc_u32 s15, s55, 0
	s_lshl_b32 s16, s60, 2
	s_lshl_b32 s17, s52, 5
	s_lshl_b32 s28, s16, 8
	s_and_b32 s38, s28, 0x400
	v_lshlrev_b32_e32 v0, 2, v162
	v_add_u32_e32 v34, s38, v0
	v_lshlrev_b32_e32 v1, 2, v34
	v_lshlrev_b32_e32 v2, 3, v162
	v_lshlrev_b32_e32 v50, 15, v34
	s_add_u32 s10, s8, 0x2000
	s_addc_u32 s11, s9, 0
	global_load_ushort v66, v50, s[10:11]
	v_add_u32_e32 v52, 0x8000, v50
	global_load_ushort v67, v52, s[10:11]
	v_add_u32_e32 v51, 0x10000, v50
	global_load_ushort v68, v51, s[10:11]
	v_add_u32_e32 v52, 0x18000, v50
	global_load_ushort v69, v52, s[10:11]
	v_add_u32_e32 v51, 0x800000, v50
	global_load_ushort v70, v51, s[10:11]
	v_add_u32_e32 v52, 0x808000, v50
	global_load_ushort v71, v52, s[10:11]
	v_add_u32_e32 v51, 0x810000, v50
	global_load_ushort v72, v51, s[10:11]
	v_add_u32_e32 v52, 0x818000, v50
	global_load_ushort v73, v52, s[10:11]
	v_add_u32_e32 v51, 0x1000000, v50
	global_load_ushort v74, v51, s[10:11]
	v_add_u32_e32 v52, 0x1008000, v50
	global_load_ushort v75, v52, s[10:11]
	v_add_u32_e32 v51, 0x1010000, v50
	global_load_ushort v76, v51, s[10:11]
	v_add_u32_e32 v52, 0x1018000, v50
	global_load_ushort v77, v52, s[10:11]
	v_add_u32_e32 v51, 0x1800000, v50
	global_load_ushort v78, v51, s[10:11]
	v_add_u32_e32 v52, 0x1808000, v50
	global_load_ushort v79, v52, s[10:11]
	v_add_u32_e32 v51, 0x1810000, v50
	global_load_ushort v80, v51, s[10:11]
	v_add_u32_e32 v52, 0x1818000, v50
	global_load_ushort v81, v52, s[10:11]
	s_waitcnt vmcnt(0)
	v_lshlrev_b32_e32 v66, 16, v66
	v_lshlrev_b32_e32 v67, 16, v67
	v_lshlrev_b32_e32 v68, 16, v68
	v_lshlrev_b32_e32 v69, 16, v69
	v_lshlrev_b32_e32 v70, 16, v70
	v_lshlrev_b32_e32 v71, 16, v71
	v_lshlrev_b32_e32 v72, 16, v72
	v_lshlrev_b32_e32 v73, 16, v73
	v_lshlrev_b32_e32 v74, 16, v74
	v_lshlrev_b32_e32 v75, 16, v75
	v_lshlrev_b32_e32 v76, 16, v76
	v_lshlrev_b32_e32 v77, 16, v77
	v_lshlrev_b32_e32 v78, 16, v78
	v_lshlrev_b32_e32 v79, 16, v79
	v_lshlrev_b32_e32 v80, 16, v80
	v_lshlrev_b32_e32 v81, 16, v81
.Ldc_loop:
	s_ashr_i32 s2, s16, 3
	s_lshl_b32 s3, s2, 13
	s_add_u32 s10, s0, s3
	s_addc_u32 s11, s1, 0
	s_add_u32 s4, s14, s3
	s_addc_u32 s5, s15, 0
	global_load_dwordx4 v[4:7], v1, s[10:11]
	global_load_dwordx4 v[20:23], v1, s[4:5]
	global_load_dwordx4 v[8:11], v1, s[10:11] offset:1024
	global_load_dwordx4 v[24:27], v1, s[4:5] offset:1024
	global_load_dwordx4 v[12:15], v1, s[10:11] offset:2048
	global_load_dwordx4 v[28:31], v1, s[4:5] offset:2048
	global_load_dwordx4 v[16:19], v1, s[10:11] offset:3072
	global_load_dwordx4 v[36:39], v1, s[4:5] offset:3072
	s_mov_b32 s28, 0x3c3504f3
	s_bitcmp1_b32 s16, 3
	s_cselect_b32 s28, 0xbc3504f3, s28
	s_lshl_b32 s3, s2, 11
	s_lshl_b32 s10, s38, 14
	s_add_i32 s3, s3, s10
	s_add_u32 s10, s6, s3
	s_addc_u32 s11, s7, 0
	s_sub_i32 s3, 0x2000, s2
	s_lshl_b32 s3, s3, 11
	s_lshl_b32 s4, s38, 14
	s_add_i32 s3, s3, s4
	s_add_u32 s4, s6, s3
	s_addc_u32 s5, s7, 0
	s_waitcnt vmcnt(6)
	v_fma_f32 v4, s28, v66, v4
	v_fma_f32 v5, s28, v67, v5
	v_fma_f32 v6, s28, v68, v6
	v_fma_f32 v7, s28, v69, v7
	v_add_f32_e32 v84, v20, v4
	v_add_f32_e32 v85, v21, v5
	v_add_f32_e32 v86, v22, v6
	v_add_f32_e32 v87, v23, v7
	v_cvt_pk_bf16_f32 v40, v84, v85
	v_cvt_pk_bf16_f32 v41, v86, v87
	global_store_dwordx2 v2, v[40:41], s[10:11]
	s_waitcnt vmcnt(5)
	v_fma_f32 v8, s28, v70, v8
	v_fma_f32 v9, s28, v71, v9
	v_fma_f32 v10, s28, v72, v10
	v_fma_f32 v11, s28, v73, v11
	v_add_f32_e32 v84, v24, v8
	v_add_f32_e32 v85, v25, v9
	v_add_f32_e32 v86, v26, v10
	v_add_f32_e32 v87, v27, v11
	v_cvt_pk_bf16_f32 v42, v84, v85
	v_cvt_pk_bf16_f32 v43, v86, v87
	global_store_dwordx2 v2, v[42:43], s[10:11] offset:512
	s_waitcnt vmcnt(4)
	v_fma_f32 v12, s28, v74, v12
	v_fma_f32 v13, s28, v75, v13
	v_fma_f32 v14, s28, v76, v14
	v_fma_f32 v15, s28, v77, v15
	v_add_f32_e32 v84, v28, v12
	v_add_f32_e32 v85, v29, v13
	v_add_f32_e32 v86, v30, v14
	v_add_f32_e32 v87, v31, v15
	v_cvt_pk_bf16_f32 v44, v84, v85
	v_cvt_pk_bf16_f32 v45, v86, v87
	global_store_dwordx2 v2, v[44:45], s[10:11] offset:1024
	s_waitcnt vmcnt(3)
	v_fma_f32 v16, s28, v78, v16
	v_fma_f32 v17, s28, v79, v17
	v_fma_f32 v18, s28, v80, v18
	v_fma_f32 v19, s28, v81, v19
	v_add_f32_e32 v84, v36, v16
	v_add_f32_e32 v85, v37, v17
	v_add_f32_e32 v86, v38, v18
	v_add_f32_e32 v87, v39, v19
	v_cvt_pk_bf16_f32 v46, v84, v85
	v_cvt_pk_bf16_f32 v47, v86, v87
	global_store_dwordx2 v2, v[46:47], s[10:11] offset:1536
	s_cmp_lt_u32 s16, 8
	s_cbranch_scc1 .Ldc_next
	v_sub_f32_e32 v84, v4, v20
	v_sub_f32_e32 v85, v5, v21
	v_sub_f32_e32 v86, v6, v22
	v_sub_f32_e32 v87, v7, v23
	v_cvt_pk_bf16_f32 v52, v84, v85
	v_cvt_pk_bf16_f32 v53, v86, v87
	global_store_dwordx2 v2, v[52:53], s[4:5]
	v_sub_f32_e32 v84, v8, v24
	v_sub_f32_e32 v85, v9, v25
	v_sub_f32_e32 v86, v10, v26
	v_sub_f32_e32 v87, v11, v27
	v_cvt_pk_bf16_f32 v54, v84, v85
	v_cvt_pk_bf16_f32 v55, v86, v87
	global_store_dwordx2 v2, v[54:55], s[4:5] offset:512
	v_sub_f32_e32 v84, v12, v28
	v_sub_f32_e32 v85, v13, v29
	v_sub_f32_e32 v86, v14, v30
	v_sub_f32_e32 v87, v15, v31
	v_cvt_pk_bf16_f32 v56, v84, v85
	v_cvt_pk_bf16_f32 v57, v86, v87
	global_store_dwordx2 v2, v[56:57], s[4:5] offset:1024
	v_sub_f32_e32 v84, v16, v36
	v_sub_f32_e32 v85, v17, v37
	v_sub_f32_e32 v86, v18, v38
	v_sub_f32_e32 v87, v19, v39
	v_cvt_pk_bf16_f32 v58, v84, v85
	v_cvt_pk_bf16_f32 v59, v86, v87
	global_store_dwordx2 v2, v[58:59], s[4:5] offset:1536
.Ldc_next:
	s_add_i32 s16, s16, s17
	s_cmpk_gt_i32 s16, 0x7fff
	s_cbranch_scc0 .Ldc_loop
